# v19 plus B-attention latent chunk trims: row-B bias pointer as row-A + 124, lane^32 bpermute index without the no-op select
# baseline (speedup 1.0000x reference)
; #define LAS3 __attribute__((address_space(3)))
; DI f32x16 qk_tile(LAS3 const char* kb, const AttnLane& L, const bf16x8& q0, const bf16x8& q1, const bf16x8& q2, const bf16x8& q3, const f32x16& init) {
;   f32x16 s = __builtin_amdgcn_mfma_f32_32x32x16_bf16(*(LAS3 const bf16x8*)(kb + L.kr0), q0, init, 0, 0, 0);
;   s = __builtin_amdgcn_mfma_f32_32x32x16_bf16(*(LAS3 const bf16x8*)(kb + L.kr1), q1, s, 0, 0, 0);
;   s = __builtin_amdgcn_mfma_f32_32x32x16_bf16(*(LAS3 const bf16x8*)(kb + L.kr2), q2, s, 0, 0, 0);
;   s = __builtin_amdgcn_mfma_f32_32x32x16_bf16(*(LAS3 const bf16x8*)(kb + L.kr3), q3, s, 0, 0, 0);
;   return s;
; }
; DI void pv_tile(LAS3 const char* vb, const AttnLane& L, const f32x16& pr, f32x16& o0, f32x16& o1) {
;   u32x4 w0, w1;
;   w0[0] = pk2(pr[0], pr[1]); w0[1] = pk2(pr[2], pr[3]); w0[2] = pk2(pr[4], pr[5]); w0[3] = pk2(pr[6], pr[7]);
;   w1[0] = pk2(pr[8], pr[9]); w1[1] = pk2(pr[10], pr[11]); w1[2] = pk2(pr[12], pr[13]); w1[3] = pk2(pr[14], pr[15]);
;   const bf16x8 pf0 = __builtin_bit_cast(bf16x8, w0), pf1 = __builtin_bit_cast(bf16x8, w1);
;   o0 = __builtin_amdgcn_mfma_f32_32x32x16_bf16(tr_pair(vb + L.vr00, vb + L.vr01), pf0, o0, 0, 0, 0);
;   o1 = __builtin_amdgcn_mfma_f32_32x32x16_bf16(tr_pair(vb + L.vr10, vb + L.vr11), pf0, o1, 0, 0, 0);
;   o0 = __builtin_amdgcn_mfma_f32_32x32x16_bf16(tr_pair(vb + 2048 + L.vr00, vb + 2048 + L.vr01), pf1, o0, 0, 0, 0);
;   o1 = __builtin_amdgcn_mfma_f32_32x32x16_bf16(tr_pair(vb + 2048 + L.vr10, vb + 2048 + L.vr11), pf1, o1, 0, 0, 0);
; }
; template <int MK> ...
;   f32x16 s0 = qk_tile(k0, L, q0, q1, q2, q3, init);
;   f32x16 s1 = qk_tile(k1, L, q0, q1, q2, q3, init);
;   if (MK == 2) {
; #pragma unroll
;     for (int v = 0; v < 16; ++v) { s0[v] += b0[(v & 3) + 8 * (v >> 2)]; s1[v] += b1[(v & 3) + 8 * (v >> 2)]; }
; template <int MODE>
; DI void attn_seq(const Params& p, int layer, char* smem, const int tid, const int nitems, bf16_t* ob, const int ostride) {
;     ...
;         const int rrA = d.a0 + 2 * (u - 2), rrB = rrA + 1;
;         const bool inA = (rrA >= wr_lo) && (rrA <= wr_hi), inB = (rrB >= wr_lo) && (rrB <= wr_hi) && (rrB <= d.a1);
;         if (inA || inB) {
;           const int rs_q = clampi(rq - 4, 0, 24);
;           const bool okA = (rrA >= rs_q) && (rrA < rs_q + 8), okB = (rrB >= rs_q) && (rrB < rs_q + 8) && (rrB <= d.a1);
.Lm1_compute:
	v_add_u32_e32 v66, s22, v183
	ds_read_b128 v[82:85], v66
	ds_read_b128 v[100:103], v66 offset:8192
	v_add_u32_e32 v86, s22, v184
	v_add_u32_e32 v87, s22, v185
	v_cmp_ge_i32_e64 s[6:7], s23, v135
	v_cmp_lt_i32_e64 s[8:9], s23, v137
	s_and_b64 s[6:7], s[6:7], s[8:9]
	s_movk_i32 s8, 0x7c
	v_cmp_ge_i32_e32 vcc, s24, v135
	s_waitcnt lgkmcnt(0)
	v_mfma_f32_32x32x16_bf16 v[66:81], v[82:85], v[128:131], v[34:49]
	ds_read_b128 v[82:85], v86
	ds_read_b128 v[104:107], v86 offset:8192
	v_add_u32_e32 v86, s22, v186
	v_cmp_lt_i32_e64 s[0:1], s24, v137
	v_readlane_b32 s9, v255, 23
	s_and_b64 vcc, vcc, s[0:1]
	ds_read_b128 v[108:111], v87 offset:8192
	s_waitcnt lgkmcnt(0)
	v_mfma_f32_32x32x16_bf16 v[66:81], v[82:85], v[124:127], v[66:81]
	ds_read_b128 v[82:85], v87
	s_waitcnt lgkmcnt(0)
	v_mfma_f32_32x32x16_bf16 v[66:81], v[82:85], v[120:123], v[66:81]
	ds_read_b128 v[82:85], v86
	ds_read_b128 v[112:115], v86 offset:8192
	s_waitcnt lgkmcnt(0)
	v_mfma_f32_32x32x16_bf16 v[66:81], v[82:85], v[116:119], v[66:81]
	v_sub_u32_e32 v82, s24, v99
	v_mul_lo_u32 v98, v82, s8
	v_add_u32_e32 v98, s20, v98
	v_add_u32_e32 v98, 0x364, v98
	v_mfma_f32_32x32x16_bf16 v[82:97], v[100:103], v[128:131], v[34:49]
	v_add_u32_e32 v101, 0x7c, v98
	v_mov_b32_e32 v100, s9
	v_cndmask_b32_e32 v98, v100, v98, vcc
	s_and_b64 vcc, s[6:7], s[88:89]
	v_mfma_f32_32x32x16_bf16 v[82:97], v[104:107], v[124:127], v[82:97]
	v_add_u32_e32 v98, v98, v168
	v_cndmask_b32_e32 v100, v100, v101, vcc
	v_add_u32_e32 v191, v100, v168
	ds_read2_b32 v[100:101], v98 offset0:15 offset1:16
	ds_read2_b32 v[102:103], v98 offset0:17 offset1:18
	ds_read2_b32 v[104:105], v98 offset0:23 offset1:24
	ds_read2_b32 v[106:107], v98 offset0:25 offset1:26
	s_waitcnt lgkmcnt(0)
	v_add_f32_e32 v102, v68, v102
	v_mfma_f32_32x32x16_bf16 v[82:97], v[108:111], v[120:123], v[82:97]
	ds_read2_b32 v[108:109], v191 offset0:15 offset1:16
	ds_read2_b32 v[110:111], v191 offset0:17 offset1:18
	ds_read2_b32 v[192:193], v191 offset0:23 offset1:24
	ds_read2_b32 v[194:195], v191 offset0:25 offset1:26
	v_add_f32_e32 v100, v66, v100
	v_add_f32_e32 v101, v67, v101
	v_add_f32_e32 v103, v69, v103
	v_add_f32_e32 v104, v70, v104
	v_add_f32_e32 v105, v71, v105
	v_add_f32_e32 v106, v72, v106
	v_mfma_f32_32x32x16_bf16 v[82:97], v[112:115], v[116:119], v[82:97]
	v_add_f32_e32 v107, v73, v107
	v_exp_f32_e32 v226, v100
	v_exp_f32_e32 v228, v101
	v_exp_f32_e32 v230, v102
	v_exp_f32_e32 v232, v103
	v_exp_f32_e32 v234, v104
	v_exp_f32_e32 v236, v105
	s_waitcnt lgkmcnt(0)
	s_nop 3
	v_add_f32_e32 v108, v82, v108
	v_add_f32_e32 v109, v83, v109
	ds_read2_b32 v[66:67], v98 offset0:31 offset1:32
	ds_read2_b32 v[68:69], v191 offset0:31 offset1:32
	ds_read2_b32 v[70:71], v98 offset0:33 offset1:34
	ds_read2_b32 v[72:73], v98 offset0:39 offset1:40
	ds_read2_b32 v[82:83], v98 offset0:41 offset1:42
	v_add_f32_e32 v110, v84, v110
	v_add_f32_e32 v111, v85, v111
	v_add_f32_e32 v196, v86, v192
	v_add_f32_e32 v213, v87, v193
	v_add_f32_e32 v221, v88, v194
	v_add_f32_e32 v225, v89, v195
	ds_read2_b32 v[84:85], v191 offset0:33 offset1:34
	ds_read2_b32 v[86:87], v191 offset0:39 offset1:40
	ds_read2_b32 v[88:89], v191 offset0:41 offset1:42
	s_waitcnt lgkmcnt(0)
	v_add_f32_e32 v191, v91, v69
	v_add_f32_e32 v69, v77, v71
	v_add_f32_e32 v71, v79, v73
	v_add_f32_e32 v98, v90, v68
	v_add_f32_e32 v68, v76, v70
	v_exp_f32_e32 v252, v71
	v_add_u32_e32 v71, s22, v188
	v_exp_f32_e32 v246, v68
	v_exp_f32_e32 v248, v69
	s_nop 0
	ds_read_b64_tr_b16 v[68:69], v71 offset:16384
	v_add_f32_e32 v70, v78, v72
	v_add_f32_e32 v72, v80, v82
	v_add_f32_e32 v73, v81, v83
	v_exp_f32_e32 v238, v106
	v_exp_f32_e32 v240, v107
	v_exp_f32_e32 v220, v72
	v_add_u32_e32 v72, s22, v189
	v_exp_f32_e32 v212, v73
	v_add_u32_e32 v73, s22, v190
	ds_read_b64_tr_b16 v[100:101], v72 offset:16384
	ds_read_b64_tr_b16 v[102:103], v73 offset:16384
	v_add_f32_e32 v66, v74, v66
	v_add_f32_e32 v67, v75, v67
	v_exp_f32_e32 v250, v70
	v_add_u32_e32 v70, s22, v187
	v_cvt_pk_bf16_f32 v192, v226, v228
	v_cvt_pk_bf16_f32 v193, v230, v232
	v_cvt_pk_bf16_f32 v194, v234, v236
	v_cvt_pk_bf16_f32 v195, v238, v240
	v_add_f32_e32 v247, v92, v84
	v_add_f32_e32 v249, v93, v85
	v_add_f32_e32 v251, v94, v86
	v_add_f32_e32 v253, v95, v87
	v_add_f32_e32 v215, v96, v88
	v_add_f32_e32 v219, v97, v89
	v_exp_f32_e32 v242, v66
	v_exp_f32_e32 v244, v67
	v_exp_f32_e32 v227, v108
	v_exp_f32_e32 v229, v109
	v_exp_f32_e32 v231, v110
	v_exp_f32_e32 v233, v111
	ds_read_b64_tr_b16 v[66:67], v70 offset:16384
	ds_read_b64_tr_b16 v[104:105], v70 offset:18432
	ds_read_b64_tr_b16 v[108:109], v70 offset:24576
	ds_read_b64_tr_b16 v[112:113], v70 offset:26624
	ds_read_b64_tr_b16 v[106:107], v71 offset:18432
	ds_read_b64_tr_b16 v[110:111], v71 offset:24576
	ds_read_b64_tr_b16 v[114:115], v71 offset:26624
	s_waitcnt lgkmcnt(6)
; #define LAS3 __attribute__((address_space(3)))
; DI unsigned pk2(float lo, float hi) { f32x2 v = {lo, hi}; return __builtin_bit_cast(unsigned, __builtin_convertvector(v, bf16x2v)); }
; DI void pv_tile(LAS3 const char* vb, const AttnLane& L, const f32x16& pr, f32x16& o0, f32x16& o1) {
;   u32x4 w0, w1;
;   w0[0] = pk2(pr[0], pr[1]); w0[1] = pk2(pr[2], pr[3]); w0[2] = pk2(pr[4], pr[5]); w0[3] = pk2(pr[6], pr[7]);
;   w1[0] = pk2(pr[8], pr[9]); w1[1] = pk2(pr[10], pr[11]); w1[2] = pk2(pr[12], pr[13]); w1[3] = pk2(pr[14], pr[15]);
;   const bf16x8 pf0 = __builtin_bit_cast(bf16x8, w0), pf1 = __builtin_bit_cast(bf16x8, w1);
;   o0 = __builtin_amdgcn_mfma_f32_32x32x16_bf16(tr_pair(vb + L.vr00, vb + L.vr01), pf0, o0, 0, 0, 0);
;   o1 = __builtin_amdgcn_mfma_f32_32x32x16_bf16(tr_pair(vb + L.vr10, vb + L.vr11), pf0, o1, 0, 0, 0);
;   o0 = __builtin_amdgcn_mfma_f32_32x32x16_bf16(tr_pair(vb + 2048 + L.vr00, vb + 2048 + L.vr01), pf1, o0, 0, 0, 0);
;   o1 = __builtin_amdgcn_mfma_f32_32x32x16_bf16(tr_pair(vb + 2048 + L.vr10, vb + 2048 + L.vr11), pf1, o1, 0, 0, 0);
; }
; template <int MK> ...
;     ...
;   const float a0 = (s0[0] + s0[1]) + (s0[2] + s0[3]), a1 = (s0[4] + s0[5]) + (s0[6] + s0[7]);
;   const float a2 = (s0[8] + s0[9]) + (s0[10] + s0[11]), a3 = (s0[12] + s0[13]) + (s0[14] + s0[15]);
;   pv_tile(v0, L, s0, st.o0, st.o1);
; #pragma unroll
;   for (int v = 0; v < 16; ++v) s1[v] = __builtin_amdgcn_exp2f(s1[v]);
;   const float a4 = (s1[0] + s1[1]) + (s1[2] + s1[3]), a5 = (s1[4] + s1[5]) + (s1[6] + s1[7]);
;   const float a6 = (s1[8] + s1[9]) + (s1[10] + s1[11]), a7 = (s1[12] + s1[13]) + (s1[14] + s1[15]);
;   pv_tile(v1, L, s1, st.o0, st.o1);
;   const float sum = ((a0 + a1) + (a2 + a3)) + ((a4 + a5) + (a6 + a7));
;   st.l += sum;
;   const float tot = sum + __shfl_xor(sum, 32);
;   if (__builtin_amdgcn_ballot_w64(tot > 256.f) != 0) {
;     const float delta = fmaxf(__builtin_amdgcn_logf(tot), 0.f);
;     const float alpha = __builtin_amdgcn_exp2f(-delta);
;     st.m += delta; st.l *= alpha;
; #pragma unroll
;     for (int v = 0; v < 16; ++v) { st.cinit[v] -= delta; st.o0[v] *= alpha; st.o1[v] *= alpha; }
;   }
	v_mfma_f32_32x32x16_bf16 v[50:65], v[66:69], v[192:195], v[50:65]
	v_exp_f32_e32 v235, v196
	ds_read_b64_tr_b16 v[196:197], v72 offset:18432
	ds_read_b64_tr_b16 v[200:201], v72 offset:24576
	ds_read_b64_tr_b16 v[204:205], v72 offset:26624
	ds_read_b64_tr_b16 v[198:199], v73 offset:18432
	ds_read_b64_tr_b16 v[202:203], v73 offset:24576
	ds_read_b64_tr_b16 v[206:207], v73 offset:26624
	v_exp_f32_e32 v237, v213
	v_exp_f32_e32 v239, v221
	v_exp_f32_e32 v241, v225
	v_exp_f32_e32 v243, v98
	v_exp_f32_e32 v245, v191
	v_mfma_f32_32x32x16_bf16 v[18:33], v[100:103], v[192:195], v[18:33]
	v_cvt_pk_bf16_f32 v100, v242, v244
	v_cvt_pk_bf16_f32 v101, v246, v248
	v_cvt_pk_bf16_f32 v102, v250, v252
	v_cvt_pk_bf16_f32 v103, v220, v212
	v_exp_f32_e32 v247, v247
	v_exp_f32_e32 v249, v249
	v_exp_f32_e32 v251, v251
	s_waitcnt lgkmcnt(8)
	v_mfma_f32_32x32x16_bf16 v[50:65], v[104:107], v[100:103], v[50:65]
	v_exp_f32_e32 v253, v253
	v_exp_f32_e32 v221, v215
	v_exp_f32_e32 v213, v219
	v_add_f32_e32 v104, v226, v228
	v_add_f32_e32 v105, v227, v229
	v_add_f32_e32 v106, v230, v232
	v_add_f32_e32 v107, v231, v233
	v_xor_b32_e32 v98, 32, v214
	v_add_f32_e32 v104, v104, v106
	v_add_f32_e32 v105, v105, v107
	s_waitcnt lgkmcnt(2)
	v_mfma_f32_32x32x16_bf16 v[18:33], v[196:199], v[100:103], v[18:33]
	v_cvt_pk_bf16_f32 v100, v227, v229
	v_cvt_pk_bf16_f32 v101, v231, v233
	v_cvt_pk_bf16_f32 v102, v235, v237
	v_cvt_pk_bf16_f32 v103, v239, v241
	v_add_f32_e64 v106, v234, v236
	v_add_f32_e64 v107, v235, v237
	v_mfma_f32_32x32x16_bf16 v[50:65], v[108:111], v[100:103], v[50:65]
	v_add_f32_e64 v108, v238, v240
	v_add_f32_e64 v109, v239, v241
	v_add_f32_e64 v110, v246, v248
	v_add_f32_e64 v111, v247, v249
	v_add_f32_e64 v106, v106, v108
	v_add_f32_e64 v107, v107, v109
	v_add_f32_e32 v108, v242, v244
	v_add_f32_e32 v109, v243, v245
	v_add_f32_e32 v104, v104, v106
	v_add_f32_e32 v105, v105, v107
	v_add_f32_e32 v108, v108, v110
	v_add_f32_e32 v109, v109, v111
	s_waitcnt lgkmcnt(1)
	v_mfma_f32_32x32x16_bf16 v[18:33], v[200:203], v[100:103], v[18:33]
	v_add_f32_e64 v100, v250, v252
	v_add_f32_e64 v101, v251, v253
	v_add_f32_e64 v102, v220, v212
	v_add_f32_e64 v103, v221, v213
	v_add_f32_e64 v110, v100, v102
	v_add_f32_e64 v111, v101, v103
	v_cvt_pk_bf16_f32 v100, v243, v245
	v_add_f32_e32 v106, v108, v110
	v_add_f32_e32 v107, v109, v111
	v_cvt_pk_bf16_f32 v101, v247, v249
	v_add_f32_e32 v104, v104, v106
	v_add_f32_e32 v105, v105, v107
	v_cvt_pk_bf16_f32 v102, v251, v253
	v_add_f32_e32 v104, v104, v105
	v_cvt_pk_bf16_f32 v103, v221, v213
	s_nop 1
	v_mfma_f32_32x32x16_bf16 v[50:65], v[112:115], v[100:103], v[50:65]
	v_lshlrev_b32_e32 v98, 2, v98
	ds_bpermute_b32 v105, v98, v104
	v_add_f32_e32 v181, v181, v104
	s_waitcnt lgkmcnt(1)
	v_mfma_f32_32x32x16_bf16 v[18:33], v[204:207], v[100:103], v[18:33]
	s_waitcnt lgkmcnt(0)
	v_add_f32_e32 v100, v104, v105
	v_cmp_lt_f32_e32 vcc, s68, v100
	s_cbranch_vccz .Lm1_cdone
	v_log_f32_e32 v100, v100
	s_nop 0
	v_max_f32_e32 v100, 0, v100
	v_exp_f32_e64 v192, -v100
	v_add_f32_e32 v182, v182, v100
	v_sub_f32_e32 v49, v49, v100
	v_sub_f32_e32 v48, v48, v100
	v_sub_f32_e32 v47, v47, v100
	v_sub_f32_e32 v46, v46, v100
	v_sub_f32_e32 v45, v45, v100
	v_mul_f32_e32 v181, v181, v192
	v_sub_f32_e32 v44, v44, v100
	v_sub_f32_e32 v43, v43, v100
	v_sub_f32_e32 v42, v42, v100
	v_sub_f32_e32 v41, v41, v100
	v_sub_f32_e32 v40, v40, v100
	v_sub_f32_e32 v39, v39, v100
	v_sub_f32_e32 v38, v38, v100
	v_sub_f32_e32 v37, v37, v100
	v_sub_f32_e32 v36, v36, v100
	v_sub_f32_e32 v35, v35, v100
	v_sub_f32_e32 v34, v34, v100
	v_pk_mul_f32 v[64:65], v[64:65], v[192:193] op_sel_hi:[1,0]
	v_pk_mul_f32 v[62:63], v[62:63], v[192:193] op_sel_hi:[1,0]
	v_pk_mul_f32 v[60:61], v[60:61], v[192:193] op_sel_hi:[1,0]
	v_pk_mul_f32 v[58:59], v[58:59], v[192:193] op_sel_hi:[1,0]
	v_pk_mul_f32 v[56:57], v[56:57], v[192:193] op_sel_hi:[1,0]
	v_pk_mul_f32 v[54:55], v[54:55], v[192:193] op_sel_hi:[1,0]
	v_pk_mul_f32 v[52:53], v[52:53], v[192:193] op_sel_hi:[1,0]
	v_pk_mul_f32 v[50:51], v[50:51], v[192:193] op_sel_hi:[1,0]
	v_pk_mul_f32 v[32:33], v[32:33], v[192:193] op_sel_hi:[1,0]
	v_pk_mul_f32 v[30:31], v[30:31], v[192:193] op_sel_hi:[1,0]
	v_pk_mul_f32 v[28:29], v[28:29], v[192:193] op_sel_hi:[1,0]
	v_pk_mul_f32 v[26:27], v[26:27], v[192:193] op_sel_hi:[1,0]
	v_pk_mul_f32 v[24:25], v[24:25], v[192:193] op_sel_hi:[1,0]
	v_pk_mul_f32 v[22:23], v[22:23], v[192:193] op_sel_hi:[1,0]
	v_pk_mul_f32 v[20:21], v[20:21], v[192:193] op_sel_hi:[1,0]
	v_pk_mul_f32 v[18:19], v[18:19], v[192:193] op_sel_hi:[1,0]
